# P0: non-temporal loads for the once-read f32 inputs (x and layer-0 w_in) so they do not evict the bf16 working set from L2/MALL
# speedup vs baseline: 1.0678x; 1.0160x over previous
; #define GAS __attribute__((address_space(1)))
; template <int GU>
; __device__ __forceinline__ void p0_transpose_item(const float* W, int N, const float* kscale, bf16* WT, int ldt, int koff, LAS float* scr, int item, int lane) {
;     const int nblk = N / 64, kb = item / nblk, nb = item % nblk, k0 = 64 * kb, n0 = 64 * nb;
;     const int q = lane >> 4, cc = lane & 15;
;     f32x4 v[16];
; #pragma unroll
;     for (int i = 0; i < 16; ++i) v[i] = *(const GAS f32x4*)(W + (size_t)(k0 + 4 * i + q) * N + n0 + 4 * cc);
;     const int c = lane & 7;
;     f32x4 s0 = (f32x4){1.f, 1.f, 1.f, 1.f}, s1 = s0;
;     if (kscale) { s0 = *(const GAS f32x4*)(kscale + k0 + 8 * c); s1 = *(const GAS f32x4*)(kscale + k0 + 8 * c + 4); }
.LBB0_18:
	s_add_i32 s4, s18, 0xfc00
	s_and_b32 s5, s4, 0xffff
	s_mul_i32 s8, s5, 0x4ec5
	s_lshr_b32 s5, s8, 20
	s_mul_i32 s5, s5, 52
	s_sub_i32 s5, s4, s5
	s_lshr_b32 s4, s8, 14
	s_and_b32 s4, s4, 0xffc0
	s_lshl_b32 s8, s5, 8
	v_or_b32_e32 v4, s4, v1
	s_and_b32 s14, s8, 0x3ff00
	v_lshl_add_u64 v[2:3], v[78:79], 0, s[14:15]
	v_mul_u32_u24_e32 v74, 0x3400, v4
	v_lshl_add_u64 v[2:3], v[2:3], 0, v[74:75]
	s_mov_b32 s8, 0xd000
	v_add_co_u32_e32 v4, vcc, s8, v2
	s_mov_b32 s8, 0x1a000
	s_nop 0
	v_addc_co_u32_e32 v5, vcc, 0, v3, vcc
	global_load_dwordx4 v[14:17], v[2:3], off nt
	global_load_dwordx4 v[10:13], v[4:5], off nt
	v_add_co_u32_e32 v4, vcc, s8, v2
	s_mov_b32 s8, 0x27000
	s_nop 0
	v_addc_co_u32_e32 v5, vcc, 0, v3, vcc
	v_add_co_u32_e32 v6, vcc, s8, v2
	s_mov_b32 s8, 0x34000
	s_nop 0
	v_addc_co_u32_e32 v7, vcc, 0, v3, vcc
	global_load_dwordx4 v[22:25], v[4:5], off nt
	global_load_dwordx4 v[18:21], v[6:7], off nt
	v_add_co_u32_e32 v4, vcc, s8, v2
	s_mov_b32 s8, 0x41000
	s_nop 0
	v_addc_co_u32_e32 v5, vcc, 0, v3, vcc
	v_add_co_u32_e32 v6, vcc, s8, v2
	s_mov_b32 s8, 0x4e000
	s_nop 0
	v_addc_co_u32_e32 v7, vcc, 0, v3, vcc
	global_load_dwordx4 v[30:33], v[4:5], off nt
	global_load_dwordx4 v[26:29], v[6:7], off nt
	v_add_co_u32_e32 v4, vcc, s8, v2
	s_mov_b32 s8, 0x5b000
	s_nop 0
	v_addc_co_u32_e32 v5, vcc, 0, v3, vcc
	v_add_co_u32_e32 v6, vcc, s8, v2
	s_mov_b32 s8, 0x68000
	s_nop 0
	v_addc_co_u32_e32 v7, vcc, 0, v3, vcc
	global_load_dwordx4 v[38:41], v[4:5], off nt
	global_load_dwordx4 v[34:37], v[6:7], off nt
	v_add_co_u32_e32 v4, vcc, s8, v2
	s_mov_b32 s8, 0x75000
	s_nop 0
	v_addc_co_u32_e32 v5, vcc, 0, v3, vcc
	v_add_co_u32_e32 v6, vcc, s8, v2
	s_lshl_b32 s8, s5, 6
	s_nop 0
	v_addc_co_u32_e32 v7, vcc, 0, v3, vcc
	global_load_dwordx4 v[46:49], v[4:5], off nt
	global_load_dwordx4 v[42:45], v[6:7], off nt
	v_add_co_u32_e32 v4, vcc, s24, v2
	s_nop 1
	v_addc_co_u32_e32 v5, vcc, 0, v3, vcc
	v_add_co_u32_e32 v6, vcc, s25, v2
	s_nop 1
	v_addc_co_u32_e32 v7, vcc, 0, v3, vcc
	global_load_dwordx4 v[54:57], v[4:5], off nt
	global_load_dwordx4 v[50:53], v[6:7], off nt
	v_add_co_u32_e32 v4, vcc, s26, v2
	s_nop 1
	v_addc_co_u32_e32 v5, vcc, 0, v3, vcc
	v_add_co_u32_e32 v6, vcc, 0xa9000, v2
	s_nop 1
	v_addc_co_u32_e32 v7, vcc, 0, v3, vcc
	global_load_dwordx4 v[62:65], v[4:5], off nt
	global_load_dwordx4 v[58:61], v[6:7], off nt
	v_add_co_u32_e32 v4, vcc, 0xb6000, v2
	s_nop 1
	v_addc_co_u32_e32 v5, vcc, 0, v3, vcc
	v_add_co_u32_e32 v2, vcc, 0xc3000, v2
	s_nop 1
	v_addc_co_u32_e32 v3, vcc, 0, v3, vcc
	global_load_dwordx4 v[70:73], v[4:5], off nt
	global_load_dwordx4 v[66:69], v[2:3], off nt
	s_and_b64 vcc, exec, s[6:7]
	s_cbranch_vccnz .LBB0_20
	s_lshl_b32 s14, s4, 2
	v_lshl_add_u64 v[6:7], v[80:81], 0, s[14:15]
	global_load_dwordx4 v[2:5], v[6:7], off offset:16 nt
	s_nop 0
	global_load_dwordx4 v[6:9], v[6:7], off nt
	s_branch .LBB0_21

; __device__ __forceinline__ void p0_pooleff_item(const float* wg, const float* scale, const float* wpb, bf16* WT, int item, int lane) {
;     ...
; #pragma unroll 1
;     for (int j0 = 0; j0 < 128; j0 += 16) {
;         float b[16];
; #pragma unroll
;         for (int u = 0; u < 16; ++u) b[u] = bp[(size_t)(j0 + u) * 1024];
; #pragma unroll
;         for (int u = 0; u < 16; ++u) { const float bb = b[u] * sp[j0 + u];
;             a0 += wgp[0 * 128 + j0 + u] * bb; a1 += wgp[1 * 128 + j0 + u] * bb; a2 += wgp[2 * 128 + j0 + u] * bb; a3 += wgp[3 * 128 + j0 + u] * bb;
;             a4 += wgp[4 * 128 + j0 + u] * bb; a5 += wgp[5 * 128 + j0 + u] * bb; a6 += wgp[6 * 128 + j0 + u] * bb; a7 += wgp[7 * 128 + j0 + u] * bb; }
.LBB0_39:
	v_add_co_u32_e32 v10, vcc, s28, v66
	s_add_u32 s4, s14, s20
	s_nop 0
	v_addc_co_u32_e32 v11, vcc, 0, v67, vcc
	v_add_co_u32_e32 v12, vcc, s29, v66
	s_addc_u32 s5, s39, s21
	s_nop 0
	v_addc_co_u32_e32 v13, vcc, 0, v67, vcc
	v_add_co_u32_e32 v84, vcc, s30, v66
	s_add_u32 s8, s40, s20
	s_nop 0
	v_addc_co_u32_e32 v85, vcc, 0, v67, vcc
	v_add_co_u32_e32 v176, vcc, s31, v66
	s_addc_u32 s9, s41, s21
	s_nop 0
	v_addc_co_u32_e32 v177, vcc, 0, v67, vcc
	v_add_co_u32_e32 v178, vcc, s34, v66
	global_load_dword v74, v[66:67], off
	global_load_dwordx4 v[2:5], v75, s[4:5] nt
	global_load_dwordx4 v[6:9], v75, s[4:5] offset:16 nt
	global_load_dwordx4 v[30:33], v75, s[4:5] offset:32 nt
	global_load_dwordx4 v[34:37], v75, s[4:5] offset:48 nt
	global_load_dword v180, v[10:11], off offset:-4096
	global_load_dword v181, v[10:11], off
	global_load_dword v182, v[12:13], off offset:-4096
	global_load_dword v183, v[12:13], off
	global_load_dwordx4 v[86:89], v75, s[8:9] nt
	global_load_dwordx4 v[104:107], v75, s[8:9] offset:512 nt
	global_load_dwordx4 v[90:93], v75, s[8:9] offset:1024 nt
	global_load_dwordx4 v[108:111], v75, s[8:9] offset:1536 nt
	global_load_dwordx4 v[112:115], v75, s[8:9] offset:2048 nt
	global_load_dwordx4 v[116:119], v75, s[8:9] offset:2560 nt
	global_load_dwordx4 v[120:123], v75, s[8:9] offset:3072 nt
	global_load_dwordx4 v[124:127], v75, s[8:9] offset:3584 nt
	s_mov_b64 s[4:5], vcc
	global_load_dwordx4 v[128:131], v75, s[8:9] offset:16 nt
	global_load_dwordx4 v[50:53], v75, s[8:9] offset:528 nt
	global_load_dwordx4 v[132:135], v75, s[8:9] offset:1040 nt
	global_load_dwordx4 v[54:57], v75, s[8:9] offset:1552 nt
	global_load_dwordx4 v[136:139], v75, s[8:9] offset:2064 nt
	global_load_dwordx4 v[58:61], v75, s[8:9] offset:2576 nt
	global_load_dwordx4 v[140:143], v75, s[8:9] offset:3088 nt
	global_load_dwordx4 v[62:65], v75, s[8:9] offset:3600 nt
	global_load_dwordx4 v[144:147], v75, s[8:9] offset:32 nt
	global_load_dwordx4 v[148:151], v75, s[8:9] offset:48 nt
	global_load_dwordx4 v[38:41], v75, s[8:9] offset:544 nt
	global_load_dwordx4 v[10:13], v75, s[8:9] offset:560 nt
	global_load_dwordx4 v[152:155], v75, s[8:9] offset:1056 nt
	global_load_dwordx4 v[156:159], v75, s[8:9] offset:1072 nt
	global_load_dwordx4 v[42:45], v75, s[8:9] offset:1568 nt
	global_load_dwordx4 v[14:17], v75, s[8:9] offset:1584 nt
	global_load_dwordx4 v[160:163], v75, s[8:9] offset:2080 nt
	global_load_dwordx4 v[164:167], v75, s[8:9] offset:2096 nt
	global_load_dwordx4 v[46:49], v75, s[8:9] offset:2592 nt
	global_load_dwordx4 v[18:21], v75, s[8:9] offset:2608 nt
	global_load_dwordx4 v[168:171], v75, s[8:9] offset:3104 nt
	global_load_dwordx4 v[172:175], v75, s[8:9] offset:3120 nt
	global_load_dwordx4 v[26:29], v75, s[8:9] offset:3616 nt
	global_load_dwordx4 v[22:25], v75, s[8:9] offset:3632 nt
	global_load_dword v195, v[84:85], off offset:-4096
	global_load_dword v196, v[84:85], off
	global_load_dword v198, v[176:177], off offset:-4096
	global_load_dword v199, v[176:177], off
	v_add_co_u32_e32 v84, vcc, s35, v66
	s_mov_b64 s[8:9], vcc
	v_addc_co_u32_e64 v179, vcc, 0, v67, s[4:5]
	v_add_co_u32_e32 v176, vcc, s36, v66
	global_load_dword v200, v[178:179], off offset:-4096
	global_load_dword v201, v[178:179], off
	v_addc_co_u32_e32 v177, vcc, 0, v67, vcc
	v_addc_co_u32_e64 v85, s[4:5], 0, v67, s[8:9]
	v_add_co_u32_e32 v178, vcc, s37, v66
	global_load_dword v202, v[84:85], off offset:-4096
	global_load_dword v203, v[84:85], off
	global_load_dword v204, v[176:177], off
	s_nop 0
	global_load_dword v177, v[176:177], off offset:-4096
	v_addc_co_u32_e32 v179, vcc, 0, v67, vcc
	global_load_dword v179, v[178:179], off
	s_add_i32 s42, s42, 16
	s_add_u32 s20, s20, 64
	s_addc_u32 s21, s21, 0
	s_cmpk_lt_u32 s42, 0x70
	v_lshl_add_u64 v[66:67], v[66:67], 0, s[16:17]
	s_waitcnt vmcnt(24)
	v_mov_b32_e32 v197, v38
	v_mov_b32_e32 v38, v145
	v_mov_b32_e32 v145, v40
	v_mov_b32_e32 v40, v147
	v_mov_b32_e32 v184, v86
	v_mov_b32_e32 v185, v104
	v_mov_b32_e32 v188, v90
	v_mov_b32_e32 v189, v108
	v_mov_b32_e32 v192, v112
	v_mul_f32_e32 v74, v74, v2
	v_mov_b32_e32 v193, v116
	v_mov_b32_e32 v116, v113
	v_mov_b32_e32 v112, v114
	v_mov_b32_e32 v113, v118
	v_mov_b32_e32 v118, v115
	v_mov_b32_e32 v114, v120
	v_mov_b32_e32 v115, v124
	v_mul_f32_e32 v176, v180, v3
	v_mov_b32_e32 v104, v87
	v_mov_b32_e32 v108, v91
	v_mov_b32_e32 v124, v121
	v_pk_fma_f32 v[82:83], v[184:185], v[74:75], v[82:83] op_sel_hi:[1,0,1]
	v_pk_fma_f32 v[72:73], v[74:75], v[188:189], v[72:73] op_sel_hi:[0,1,1]
	v_pk_fma_f32 v[70:71], v[74:75], v[192:193], v[70:71] op_sel_hi:[0,1,1]
	v_pk_fma_f32 v[68:69], v[74:75], v[114:115], v[68:69] op_sel_hi:[0,1,1]
	v_mul_f32_e32 v178, v181, v4
	v_mov_b32_e32 v186, v88
	v_mov_b32_e32 v187, v106
	v_mov_b32_e32 v190, v92
	v_mov_b32_e32 v191, v110
	v_mov_b32_e32 v120, v122
	v_mov_b32_e32 v121, v126
	s_waitcnt vmcnt(1)
	v_pk_fma_f32 v[82:83], v[104:105], v[176:177], v[82:83] op_sel_hi:[1,0,1]
	v_pk_fma_f32 v[72:73], v[176:177], v[108:109], v[72:73] op_sel_hi:[0,1,1]
	v_pk_fma_f32 v[70:71], v[176:177], v[116:117], v[70:71] op_sel_hi:[0,1,1]
	v_pk_fma_f32 v[68:69], v[176:177], v[124:125], v[68:69] op_sel_hi:[0,1,1]
	v_mul_f32_e32 v180, v182, v5
	v_mov_b32_e32 v106, v89
	v_mov_b32_e32 v110, v93
	v_mov_b32_e32 v126, v123
	s_waitcnt vmcnt(0)
; #define GAS __attribute__((address_space(1)))
; __device__ __forceinline__ unsigned pk2(float lo, float hi) { f32x2p v = {lo, hi}; bf16x2p b = __builtin_convertvector(v, bf16x2p); return __builtin_bit_cast(unsigned, b); }
; __device__ __forceinline__ void p0_pooleff_item(const float* wg, const float* scale, const float* wpb, bf16* WT, int item, int lane) {
;     ...
; #pragma unroll 1
;     for (int j0 = 0; j0 < 128; j0 += 16) {
;         float b[16];
; #pragma unroll
;         for (int u = 0; u < 16; ++u) b[u] = bp[(size_t)(j0 + u) * 1024];
; #pragma unroll
;         for (int u = 0; u < 16; ++u) { const float bb = b[u] * sp[j0 + u];
;             a0 += wgp[0 * 128 + j0 + u] * bb; a1 += wgp[1 * 128 + j0 + u] * bb; a2 += wgp[2 * 128 + j0 + u] * bb; a3 += wgp[3 * 128 + j0 + u] * bb;
;             a4 += wgp[4 * 128 + j0 + u] * bb; a5 += wgp[5 * 128 + j0 + u] * bb; a6 += wgp[6 * 128 + j0 + u] * bb; a7 += wgp[7 * 128 + j0 + u] * bb; }
;     }
;     v4u o; o.x = pk2(a0, a1); o.y = pk2(a2, a3); o.z = pk2(a4, a5); o.w = pk2(a6, a7);
;     *(GAS v4u*)(WT + (size_t)n * 1024 + g * 128 + cblk * 8) = o;
	v_pk_fma_f32 v[82:83], v[186:187], v[178:179], v[82:83] op_sel_hi:[1,0,1]
	v_pk_fma_f32 v[72:73], v[178:179], v[190:191], v[72:73] op_sel_hi:[0,1,1]
	v_pk_fma_f32 v[70:71], v[178:179], v[112:113], v[70:71] op_sel_hi:[0,1,1]
	v_pk_fma_f32 v[68:69], v[178:179], v[120:121], v[68:69] op_sel_hi:[0,1,1]
	v_mul_f32_e32 v182, v183, v6
	v_mov_b32_e32 v122, v128
	v_mov_b32_e32 v123, v50
	v_mov_b32_e32 v50, v129
	v_mov_b32_e32 v128, v130
	v_mov_b32_e32 v129, v52
	v_mov_b32_e32 v52, v131
	v_mov_b32_e32 v130, v132
	v_mov_b32_e32 v131, v54
	v_mov_b32_e32 v54, v133
	v_mov_b32_e32 v132, v134
	v_mov_b32_e32 v133, v56
	v_mov_b32_e32 v56, v135
	v_mov_b32_e32 v134, v136
	v_mov_b32_e32 v135, v58
	v_mov_b32_e32 v58, v137
	v_mov_b32_e32 v136, v138
	v_mov_b32_e32 v137, v60
	v_mov_b32_e32 v60, v139
	v_mov_b32_e32 v138, v140
	v_mov_b32_e32 v139, v62
	v_pk_fma_f32 v[82:83], v[106:107], v[180:181], v[82:83] op_sel_hi:[1,0,1]
	v_pk_fma_f32 v[72:73], v[180:181], v[110:111], v[72:73] op_sel_hi:[0,1,1]
	v_pk_fma_f32 v[70:71], v[180:181], v[118:119], v[70:71] op_sel_hi:[0,1,1]
	v_pk_fma_f32 v[68:69], v[180:181], v[126:127], v[68:69] op_sel_hi:[0,1,1]
	v_mov_b32_e32 v62, v141
	v_mov_b32_e32 v140, v142
	v_mul_f32_e32 v142, v195, v7
	v_pk_fma_f32 v[82:83], v[122:123], v[182:183], v[82:83] op_sel_hi:[1,0,1]
	v_pk_fma_f32 v[72:73], v[182:183], v[130:131], v[72:73] op_sel_hi:[0,1,1]
	v_pk_fma_f32 v[70:71], v[182:183], v[134:135], v[70:71] op_sel_hi:[0,1,1]
	v_pk_fma_f32 v[68:69], v[182:183], v[138:139], v[68:69] op_sel_hi:[0,1,1]
	v_mov_b32_e32 v141, v64
	v_mul_f32_e32 v8, v196, v8
	v_pk_fma_f32 v[50:51], v[50:51], v[142:143], v[82:83] op_sel_hi:[1,0,1]
	v_pk_fma_f32 v[54:55], v[142:143], v[54:55], v[72:73] op_sel_hi:[0,1,1]
	v_pk_fma_f32 v[58:59], v[142:143], v[58:59], v[70:71] op_sel_hi:[0,1,1]
	v_pk_fma_f32 v[62:63], v[142:143], v[62:63], v[68:69] op_sel_hi:[0,1,1]
	v_mov_b32_e32 v64, v143
	v_mul_f32_e32 v74, v198, v9
	v_pk_fma_f32 v[50:51], v[128:129], v[8:9], v[50:51] op_sel_hi:[1,0,1]
	v_pk_fma_f32 v[54:55], v[8:9], v[132:133], v[54:55] op_sel_hi:[0,1,1]
	v_pk_fma_f32 v[58:59], v[8:9], v[136:137], v[58:59] op_sel_hi:[0,1,1]
	v_pk_fma_f32 v[8:9], v[8:9], v[140:141], v[62:63] op_sel_hi:[0,1,1]
	v_mov_b32_e32 v196, v144
	v_mov_b32_e32 v144, v146
	v_mov_b32_e32 v4, v148
	v_mov_b32_e32 v5, v10
	v_mov_b32_e32 v10, v149
	v_mov_b32_e32 v2, v150
	v_mov_b32_e32 v3, v12
	v_mov_b32_e32 v12, v151
	v_mov_b32_e32 v146, v152
	v_mov_b32_e32 v147, v42
	v_mov_b32_e32 v148, v154
	v_mov_b32_e32 v149, v44
	v_mov_b32_e32 v44, v155
	v_mov_b32_e32 v150, v160
	v_mov_b32_e32 v151, v46
	v_mov_b32_e32 v154, v168
	v_mov_b32_e32 v155, v26
	v_mul_f32_e32 v30, v199, v30
	v_pk_fma_f32 v[50:51], v[52:53], v[74:75], v[50:51] op_sel_hi:[1,0,1]
	v_pk_fma_f32 v[52:53], v[74:75], v[56:57], v[54:55] op_sel_hi:[0,1,1]
	v_pk_fma_f32 v[54:55], v[74:75], v[60:61], v[58:59] op_sel_hi:[0,1,1]
	v_pk_fma_f32 v[8:9], v[74:75], v[64:65], v[8:9] op_sel_hi:[0,1,1]
	v_mov_b32_e32 v42, v153
	v_mov_b32_e32 v46, v161
	v_mov_b32_e32 v26, v169
	v_mul_f32_e32 v104, v200, v31
	v_pk_fma_f32 v[50:51], v[196:197], v[30:31], v[50:51] op_sel_hi:[1,0,1]
	v_pk_fma_f32 v[52:53], v[30:31], v[146:147], v[52:53] op_sel_hi:[0,1,1]
	v_pk_fma_f32 v[54:55], v[30:31], v[150:151], v[54:55] op_sel_hi:[0,1,1]
	v_pk_fma_f32 v[8:9], v[30:31], v[154:155], v[8:9] op_sel_hi:[0,1,1]
	v_mov_b32_e32 v84, v156
	v_mov_b32_e32 v85, v14
	v_mov_b32_e32 v14, v157
	v_mov_b32_e32 v152, v162
	v_mov_b32_e32 v153, v48
	v_mov_b32_e32 v156, v170
	v_mov_b32_e32 v157, v28
	v_mul_f32_e32 v32, v201, v32
	v_pk_fma_f32 v[30:31], v[38:39], v[104:105], v[50:51] op_sel_hi:[1,0,1]
	v_pk_fma_f32 v[38:39], v[104:105], v[42:43], v[52:53] op_sel_hi:[0,1,1]
	v_pk_fma_f32 v[42:43], v[104:105], v[46:47], v[54:55] op_sel_hi:[0,1,1]
	v_pk_fma_f32 v[8:9], v[104:105], v[26:27], v[8:9] op_sel_hi:[0,1,1]
	v_mov_b32_e32 v48, v163
	v_mov_b32_e32 v28, v171
	v_mul_f32_e32 v108, v202, v33
	v_pk_fma_f32 v[26:27], v[144:145], v[32:33], v[30:31] op_sel_hi:[1,0,1]
	v_pk_fma_f32 v[30:31], v[32:33], v[148:149], v[38:39] op_sel_hi:[0,1,1]
	v_pk_fma_f32 v[38:39], v[32:33], v[152:153], v[42:43] op_sel_hi:[0,1,1]
	v_pk_fma_f32 v[8:9], v[32:33], v[156:157], v[8:9] op_sel_hi:[0,1,1]
	v_mov_b32_e32 v88, v164
	v_mov_b32_e32 v89, v18
	v_mov_b32_e32 v92, v172
	v_mov_b32_e32 v93, v22
	v_mul_f32_e32 v34, v203, v34
	v_pk_fma_f32 v[26:27], v[40:41], v[108:109], v[26:27] op_sel_hi:[1,0,1]
	v_pk_fma_f32 v[30:31], v[108:109], v[44:45], v[30:31] op_sel_hi:[0,1,1]
	v_pk_fma_f32 v[32:33], v[108:109], v[48:49], v[38:39] op_sel_hi:[0,1,1]
	v_pk_fma_f32 v[8:9], v[108:109], v[28:29], v[8:9] op_sel_hi:[0,1,1]
	v_mov_b32_e32 v18, v165
	v_mov_b32_e32 v22, v173
	v_mul_f32_e32 v106, v177, v35
	v_pk_fma_f32 v[4:5], v[4:5], v[34:35], v[26:27] op_sel_hi:[1,0,1]
	v_pk_fma_f32 v[26:27], v[34:35], v[84:85], v[30:31] op_sel_hi:[0,1,1]
	v_pk_fma_f32 v[28:29], v[34:35], v[88:89], v[32:33] op_sel_hi:[0,1,1]
	v_pk_fma_f32 v[8:9], v[34:35], v[92:93], v[8:9] op_sel_hi:[0,1,1]
	v_mov_b32_e32 v6, v158
	v_mov_b32_e32 v7, v16
	v_mov_b32_e32 v86, v166
	v_mov_b32_e32 v87, v20
	v_mov_b32_e32 v90, v174
	v_mov_b32_e32 v91, v24
	v_mul_f32_e32 v36, v204, v36
	v_pk_fma_f32 v[4:5], v[10:11], v[106:107], v[4:5] op_sel_hi:[1,0,1]
	v_pk_fma_f32 v[10:11], v[106:107], v[14:15], v[26:27] op_sel_hi:[0,1,1]
	v_pk_fma_f32 v[14:15], v[106:107], v[18:19], v[28:29] op_sel_hi:[0,1,1]
	v_pk_fma_f32 v[8:9], v[106:107], v[22:23], v[8:9] op_sel_hi:[0,1,1]
	v_mov_b32_e32 v16, v159
	v_mov_b32_e32 v20, v167
	v_mov_b32_e32 v24, v175
	v_mul_f32_e32 v110, v179, v37
	v_pk_fma_f32 v[2:3], v[2:3], v[36:37], v[4:5] op_sel_hi:[1,0,1]
	v_pk_fma_f32 v[4:5], v[36:37], v[6:7], v[10:11] op_sel_hi:[0,1,1]
	v_pk_fma_f32 v[6:7], v[36:37], v[86:87], v[14:15] op_sel_hi:[0,1,1]
	v_pk_fma_f32 v[8:9], v[36:37], v[90:91], v[8:9] op_sel_hi:[0,1,1]
	v_pk_fma_f32 v[82:83], v[12:13], v[110:111], v[2:3] op_sel_hi:[1,0,1]
	v_pk_fma_f32 v[72:73], v[110:111], v[16:17], v[4:5] op_sel_hi:[0,1,1]
	v_pk_fma_f32 v[70:71], v[110:111], v[20:21], v[6:7] op_sel_hi:[0,1,1]
	v_pk_fma_f32 v[68:69], v[110:111], v[24:25], v[8:9] op_sel_hi:[0,1,1]
	s_cbranch_scc1 .LBB0_39
	s_lshl_b32 s4, s38, 6
	s_and_b32 s4, s4, 0x3c0
	v_or_b32_e32 v6, s4, v194
	v_lshlrev_b32_e32 v74, 11, v6
	v_lshl_add_u64 v[6:7], s[12:13], 0, v[74:75]
	v_lshl_add_u64 v[6:7], s[18:19], 1, v[6:7]
	s_and_b32 s14, s38, 0xf0
	v_cvt_pk_bf16_f32 v2, v82, v83
	v_cvt_pk_bf16_f32 v3, v72, v73
	v_cvt_pk_bf16_f32 v4, v70, v71
	v_cvt_pk_bf16_f32 v5, v68, v69
	v_lshl_add_u64 v[6:7], v[6:7], 0, s[14:15]
	global_store_dwordx4 v[6:7], v[2:5], off
	s_branch .LBB0_15

; #define GAS __attribute__((address_space(1)))
; __device__ __forceinline__ unsigned pk2(float lo, float hi) { f32x2p v = {lo, hi}; bf16x2p b = __builtin_convertvector(v, bf16x2p); return __builtin_bit_cast(unsigned, b); }
; __global__ void __launch_bounds__(NWAVES * 64, 2) mk_fwd(Args args) {
;     ...
;         for (int m = gw; m < M; m += 2 * NGW) {
;             const int m1 = m + NGW;
;             const bool has1 = m1 < M;
;             const GAS f32x4* xr0 = (const GAS f32x4*)(x + (size_t)m * DM) + lane;
;             const GAS f32x4* xr1 = (const GAS f32x4*)(x + (size_t)(has1 ? m1 : m) * DM) + lane;
;             f32x4 v0[4], v1[4]; float s0 = 0.f, s1 = 0.f;
; #pragma unroll
;             for (int j = 0; j < 4; ++j) { v0[j] = xr0[64 * j]; v1[j] = xr1[64 * j]; }
; #pragma unroll
;             for (int j = 0; j < 4; ++j) { s0 += (v0[j].x * v0[j].x + v0[j].y * v0[j].y) + (v0[j].z * v0[j].z + v0[j].w * v0[j].w); s1 += (v1[j].x * v1[j].x + v1[j].y * v1[j].y) + (v1[j].z * v1[j].z + v1[j].w * v1[j].w); }
;             s0 = wave_sum(s0); s1 = wave_sum(s1);
;             GAS unsigned long long* o0 = (GAS unsigned long long*)(HB + (size_t)m * DM) + lane;
; #pragma unroll
;             for (int j = 0; j < 4; ++j) o0[64 * j] = (unsigned long long)pk2(v0[j].x, v0[j].y) | ((unsigned long long)pk2(v0[j].z, v0[j].w) << 32);
;             if (lane == 0) ssq[m] = s0;
;             if (has1) {
;                 GAS unsigned long long* o1 = (GAS unsigned long long*)(HB + (size_t)m1 * DM) + lane;
; #pragma unroll
;                 for (int j = 0; j < 4; ++j) o1[64 * j] = (unsigned long long)pk2(v1[j].x, v1[j].y) | ((unsigned long long)pk2(v1[j].z, v1[j].w) << 32);
;                 if (lane == 0) ssq[m1] = s1;
;             }
;         }
.LBB0_45:
	s_ashr_i32 s9, s8, 31
	s_lshl_b64 s[6:7], s[8:9], 12
	v_lshl_add_u64 v[2:3], v[20:21], 0, s[6:7]
	s_add_i32 s6, s8, s55
	s_cmpk_lt_i32 s6, 0x4000
	s_cselect_b64 s[12:13], -1, 0
	s_waitcnt lgkmcnt(1)
	global_load_dwordx4 v[30:33], v[2:3], off nt
	global_load_dwordx4 v[34:37], v[2:3], off offset:1024 nt
	global_load_dwordx4 v[38:41], v[2:3], off offset:2048 nt
	global_load_dwordx4 v[42:45], v[2:3], off offset:3072 nt
	s_and_b64 s[14:15], s[12:13], exec
	s_cselect_b32 s14, s6, s8
	s_ashr_i32 s15, s14, 31
	s_lshl_b64 s[14:15], s[14:15], 12
	v_lshl_add_u64 v[2:3], v[20:21], 0, s[14:15]
	global_load_dwordx4 v[14:17], v[2:3], off nt
	global_load_dwordx4 v[10:13], v[2:3], off offset:1024 nt
	global_load_dwordx4 v[6:9], v[2:3], off offset:2048 nt
	s_nop 0
	global_load_dwordx4 v[2:5], v[2:3], off offset:3072 nt
	s_lshl_b64 s[14:15], s[8:9], 11
	s_waitcnt vmcnt(7)
	v_mul_f32_e32 v18, v31, v31
	s_waitcnt lgkmcnt(0)
	v_mul_f32_e32 v29, v33, v33
	s_waitcnt vmcnt(6)
	v_mul_f32_e32 v46, v35, v35
	v_mul_f32_e32 v47, v37, v37
	s_waitcnt vmcnt(5)
	v_mul_f32_e32 v48, v39, v39
	v_mul_f32_e32 v49, v41, v41
	v_fmac_f32_e32 v18, v30, v30
	v_fmac_f32_e32 v29, v32, v32
	v_fmac_f32_e32 v46, v34, v34
	v_fmac_f32_e32 v47, v36, v36
	s_waitcnt vmcnt(4)
	v_mul_f32_e32 v50, v43, v43
	v_mul_f32_e32 v51, v45, v45
	v_fmac_f32_e32 v48, v38, v38
	v_fmac_f32_e32 v49, v40, v40
	v_add_f32_e32 v18, v18, v29
	v_add_f32_e32 v29, v46, v47
	v_fmac_f32_e32 v50, v42, v42
	v_fmac_f32_e32 v51, v44, v44
	v_add_f32_e32 v46, v48, v49
	v_add_f32_e32 v18, v18, v29
	v_add_f32_e32 v47, v50, v51
	v_add_f32_e32 v18, v18, v46
	v_add_f32_e32 v18, v18, v47
	s_waitcnt vmcnt(3)
	v_mul_f32_e32 v29, v15, v15
	v_mul_f32_e32 v46, v17, v17
	s_waitcnt vmcnt(2)
	v_mul_f32_e32 v47, v11, v11
	v_mul_f32_e32 v48, v13, v13
	s_waitcnt vmcnt(1)
	v_mul_f32_e32 v49, v7, v7
	v_mul_f32_e32 v50, v9, v9
	v_fmac_f32_e32 v29, v14, v14
	v_fmac_f32_e32 v46, v16, v16
	v_fmac_f32_e32 v47, v10, v10
	v_fmac_f32_e32 v48, v12, v12
	s_waitcnt vmcnt(0)
	v_mul_f32_e32 v51, v3, v3
	v_mul_f32_e32 v52, v5, v5
	v_fmac_f32_e32 v49, v6, v6
	v_fmac_f32_e32 v50, v8, v8
	v_add_f32_e32 v29, v29, v46
	v_add_f32_e32 v46, v47, v48
	v_fmac_f32_e32 v51, v2, v2
	v_fmac_f32_e32 v52, v4, v4
	v_add_f32_e32 v47, v49, v50
	v_add_f32_e32 v29, v29, v46
	v_add_f32_e32 v48, v51, v52
	v_add_f32_e32 v29, v29, v47
	v_add_f32_e32 v29, v29, v48
	ds_bpermute_b32 v53, v1, v18
	ds_bpermute_b32 v46, v1, v29
	v_cvt_pk_bf16_f32 v30, v30, v31
	v_cvt_pk_bf16_f32 v31, v32, v33
	v_cvt_pk_bf16_f32 v32, v34, v35
	s_waitcnt lgkmcnt(1)
	v_add_f32_e32 v18, v18, v53
	s_waitcnt lgkmcnt(0)
	v_add_f32_e32 v29, v29, v46
	ds_bpermute_b32 v48, v24, v18
	ds_bpermute_b32 v49, v24, v29
	v_cvt_pk_bf16_f32 v33, v36, v37
	v_lshl_add_u64 v[46:47], v[22:23], 0, s[14:15]
	global_store_dwordx2 v[46:47], v[30:31], off
	global_store_dwordx2 v[46:47], v[32:33], off offset:512
	s_waitcnt lgkmcnt(1)
	v_add_f32_e32 v18, v18, v48
	s_waitcnt lgkmcnt(0)
	v_add_f32_e32 v29, v29, v49
	ds_bpermute_b32 v48, v25, v18
	ds_bpermute_b32 v49, v25, v29
	v_cvt_pk_bf16_f32 v34, v38, v39
	v_cvt_pk_bf16_f32 v32, v42, v43
	v_cvt_pk_bf16_f32 v33, v44, v45
	s_waitcnt lgkmcnt(1)
	v_add_f32_e32 v18, v18, v48
	s_waitcnt lgkmcnt(0)
	v_add_f32_e32 v29, v29, v49
	ds_bpermute_b32 v35, v26, v18
	ds_bpermute_b32 v48, v26, v29
	global_store_dwordx2 v[46:47], v[32:33], off offset:1536
	s_waitcnt lgkmcnt(1)
	v_add_f32_e32 v18, v18, v35
	s_waitcnt lgkmcnt(0)
	v_add_f32_e32 v29, v29, v48
	ds_bpermute_b32 v35, v27, v18
	ds_bpermute_b32 v36, v27, v29
	s_waitcnt lgkmcnt(1)
	v_add_f32_e32 v30, v18, v35
	s_waitcnt lgkmcnt(0)
	v_add_f32_e32 v18, v29, v36
	ds_bpermute_b32 v31, v28, v30
	ds_bpermute_b32 v29, v28, v18
	v_cvt_pk_bf16_f32 v35, v40, v41
	global_store_dwordx2 v[46:47], v[34:35], off offset:1024
	s_and_saveexec_b64 s[14:15], s[4:5]
	s_cbranch_execnz .LBB0_47
	s_or_b64 exec, exec, s[14:15]
	s_andn2_b64 vcc, exec, s[12:13]
	s_cbranch_vccnz .LBB0_44
	s_branch .LBB0_48
